# GEMM K-loops: removed the no-op s_setprio 0 / s_setprio 1 pairs between the two MFMA blocks of each super-phase (A/B of the priority flips)
# baseline (speedup 1.0000x reference)
; #define PG8_STAGE(bufoff, gbase, voff) do { _Pragma("unroll") for (int _i = 0; _i < 2; ++_i) \
;         __builtin_amdgcn_global_load_lds((const unsigned*)((const char*)(gbase) + (voff)[_i]), (PG8_LAS unsigned*)(lds + (bufoff) + ldsw + _i * 8192), 16, 0, 0); } while (0)
; #define PG8_LDA(dst, b, h) do { _Pragma("unroll") for (int m = 0; m < 4; ++m) _Pragma("unroll") for (int k = 0; k < 2; ++k) dst[m][k] = *(const PG8_LAS bf16x8*)(lds + PG8_SA(b, h) + aoff + m * 2048 + k * 1024); } while (0)
; #define PG8_LDB(dst, b, h) do { _Pragma("unroll") for (int n = 0; n < 2; ++n) _Pragma("unroll") for (int k = 0; k < 2; ++k) dst[n][k] = *(const PG8_LAS bf16x8*)(lds + PG8_SB(b, h) + boff + n * 2048 + k * 1024); } while (0)
; #define PG8_MMA(ai, bj, At, Bt) do { __builtin_amdgcn_s_setprio(1); _Pragma("unroll") for (int m = 0; m < 4; ++m) _Pragma("unroll") for (int n = 0; n < 2; ++n) _Pragma("unroll") for (int k = 0; k < 2; ++k) \
;         acc[ai][bj][m][n] = __builtin_amdgcn_mfma_f32_16x16x32_bf16(Bt[n][k], At[m][k], acc[ai][bj][m][n], 0, 0, 0); __builtin_amdgcn_s_setprio(0); } while (0)
; #define PG8_WAIT_V(n) asm volatile("s_waitcnt vmcnt(" #n ")" ::: "memory")
; #define PG8_BAR __builtin_amdgcn_s_barrier()
; template <class Epi, class Sched, bool ALIGN_EPI = false, bool SP2 = false>
; __device__ __forceinline__ void gemm_phase(PG8_LAS unsigned char* lds, const Gemm g, const Sched& S, const Epi& E) {
;     ...
;         for (int t = 0; t < nt; t += 2) {
;             const bool last = (t == nt - 2);
;             const char* a1 = cA + (size_t)(t + 1) * kstep;
;             const char* a2 = last ? nA : cA + (size_t)(t + 2) * kstep; const char* b2 = last ? nB : cB + (size_t)(t + 2) * kstep;
;             const char* a3 = a2 + kstep; const char* b3 = b2 + kstep;
;             if (last && has_next) S.a_ready(nxt);
;             if constexpr (SP2) {
;             PG8_LDB(B0, 0, 0); PG8_LDB(B1, 0, 1); PG8_SCHED; PG8_LDA(At, 0, 0); PG8_STAGE(PG8_SA(1, 1), a1 + hstepA, voffA);
;             PG8_WAIT_V(8); PG8_WAIT_L(0); PG8_BAR; PG8_MMA(0, 0, At, B0); PG8_MMA(0, 1, At, B1); PG8_BAR; PG8_SCHED;
;             PG8_LDA(At, 0, 1); PG8_STAGE(PG8_SB(0, 0), b2, voffB); PG8_STAGE(PG8_SB(0, 1), b2 + hstep, voffB); PG8_STAGE(PG8_SA(0, 0), a2, voffA);
;             PG8_WAIT_V(8); PG8_WAIT_L(0); PG8_BAR; PG8_MMA(1, 0, At, B0); PG8_MMA(1, 1, At, B1); PG8_BAR; PG8_SCHED;
.LBB0_716:
	s_add_i32 s46, s28, 2
	s_add_u32 s34, s0, 0x80
	s_addc_u32 s35, s1, 0
	s_add_i32 s47, 0, 0x10000
	s_cmp_eq_u32 s83, s28
	s_cselect_b32 s45, s49, s35
	s_cselect_b32 s44, s48, s34
	s_cselect_b32 s57, s55, s21
	s_cselect_b32 s56, s54, s20
	s_add_i32 s28, 0, 0x14000
	v_add_u32_e32 v160, s47, v179
	v_add_u32_e32 v168, s28, v179
	ds_read_b128 v[148:151], v160
	ds_read_b128 v[152:155], v160 offset:1024
	ds_read_b128 v[156:159], v160 offset:2048
	ds_read_b128 v[160:163], v160 offset:3072
	ds_read_b128 v[164:167], v168
	ds_read_b128 v[172:175], v168 offset:1024
	ds_read_b128 v[182:185], v168 offset:2048
	ds_read_b128 v[186:189], v168 offset:3072
	v_lshl_add_u64 v[176:177], s[0:1], 0, v[144:145]
	s_add_i32 m0, s63, 0xc000
	ds_read_b128 v[190:193], v180
	ds_read_b128 v[194:197], v180 offset:1024
	ds_read_b128 v[218:221], v180 offset:2048
	ds_read_b128 v[222:225], v180 offset:3072
	ds_read_b128 v[226:229], v180 offset:4096
	ds_read_b128 v[230:233], v180 offset:5120
	ds_read_b128 v[234:237], v180 offset:6144
	ds_read_b128 v[238:241], v180 offset:7168
	global_load_lds_dwordx4 v[176:177], off
	v_lshl_add_u64 v[176:177], s[0:1], 0, v[146:147]
	s_add_i32 m0, s63, 0xe000
	s_nop 0
	global_load_lds_dwordx4 v[176:177], off
	s_waitcnt vmcnt(8)
	s_waitcnt lgkmcnt(0)
	s_barrier
	s_setprio 1
	s_waitcnt lgkmcnt(0)
	v_mfma_f32_16x16x32_bf16 v[124:127], v[148:151], v[190:193], v[124:127]
	v_mfma_f32_16x16x32_bf16 v[120:123], v[156:159], v[190:193], v[120:123]
	v_mfma_f32_16x16x32_bf16 v[108:111], v[148:151], v[218:221], v[108:111]
	v_mfma_f32_16x16x32_bf16 v[104:107], v[156:159], v[218:221], v[104:107]
	v_mfma_f32_16x16x32_bf16 v[92:95], v[148:151], v[226:229], v[92:95]
	v_mfma_f32_16x16x32_bf16 v[88:91], v[156:159], v[226:229], v[88:91]
	v_mfma_f32_16x16x32_bf16 v[76:79], v[148:151], v[234:237], v[76:79]
	v_mfma_f32_16x16x32_bf16 v[72:75], v[156:159], v[234:237], v[72:75]
	v_mfma_f32_16x16x32_bf16 v[124:127], v[152:155], v[194:197], v[124:127]
	v_mfma_f32_16x16x32_bf16 v[120:123], v[160:163], v[194:197], v[120:123]
	v_mfma_f32_16x16x32_bf16 v[108:111], v[152:155], v[222:225], v[108:111]
	v_mfma_f32_16x16x32_bf16 v[104:107], v[160:163], v[222:225], v[104:107]
	v_mfma_f32_16x16x32_bf16 v[92:95], v[152:155], v[230:233], v[92:95]
	v_mfma_f32_16x16x32_bf16 v[88:91], v[160:163], v[230:233], v[88:91]
	v_mfma_f32_16x16x32_bf16 v[76:79], v[152:155], v[238:241], v[76:79]
	v_mfma_f32_16x16x32_bf16 v[72:75], v[160:163], v[238:241], v[72:75]
	v_mfma_f32_16x16x32_bf16 v[116:119], v[164:167], v[190:193], v[116:119]
	v_mfma_f32_16x16x32_bf16 v[112:115], v[182:185], v[190:193], v[112:115]
	v_mfma_f32_16x16x32_bf16 v[100:103], v[164:167], v[218:221], v[100:103]
	v_mfma_f32_16x16x32_bf16 v[96:99], v[182:185], v[218:221], v[96:99]
	v_mfma_f32_16x16x32_bf16 v[84:87], v[164:167], v[226:229], v[84:87]
	v_mfma_f32_16x16x32_bf16 v[80:83], v[182:185], v[226:229], v[80:83]
	v_mfma_f32_16x16x32_bf16 v[68:71], v[164:167], v[234:237], v[68:71]
	v_mfma_f32_16x16x32_bf16 v[64:67], v[182:185], v[234:237], v[64:67]
	v_mfma_f32_16x16x32_bf16 v[116:119], v[172:175], v[194:197], v[116:119]
	v_mfma_f32_16x16x32_bf16 v[112:115], v[186:189], v[194:197], v[112:115]
	v_mfma_f32_16x16x32_bf16 v[100:103], v[172:175], v[222:225], v[100:103]
	v_mfma_f32_16x16x32_bf16 v[96:99], v[186:189], v[222:225], v[96:99]
	v_mfma_f32_16x16x32_bf16 v[84:87], v[172:175], v[230:233], v[84:87]
	v_mfma_f32_16x16x32_bf16 v[80:83], v[186:189], v[230:233], v[80:83]
	v_mfma_f32_16x16x32_bf16 v[68:71], v[172:175], v[238:241], v[68:71]
	v_mfma_f32_16x16x32_bf16 v[64:67], v[186:189], v[238:241], v[64:67]
	s_setprio 0
	s_barrier
	s_add_i32 s34, s47, s62
	v_lshl_add_u64 v[176:177], s[56:57], 0, v[130:131]
	s_mov_b32 m0, s34
	ds_read_b128 v[190:193], v180 offset:16384
	ds_read_b128 v[194:197], v180 offset:17408
	ds_read_b128 v[218:221], v180 offset:18432
	ds_read_b128 v[222:225], v180 offset:19456
	ds_read_b128 v[226:229], v180 offset:20480
	ds_read_b128 v[230:233], v180 offset:21504
	ds_read_b128 v[234:237], v180 offset:22528
	ds_read_b128 v[238:241], v180 offset:23552
	global_load_lds_dwordx4 v[176:177], off
	s_add_i32 m0, s34, 0x2000
	v_lshl_add_u64 v[210:211], s[56:57], 0, v[134:135]
	s_add_u32 s56, s56, s60
	s_addc_u32 s57, s57, 0
	s_add_i32 s28, s28, s62
	global_load_lds_dwordx4 v[210:211], off
	v_lshl_add_u64 v[212:213], s[56:57], 0, v[130:131]
	s_mov_b32 m0, s28
	v_lshl_add_u64 v[242:243], s[56:57], 0, v[134:135]
	global_load_lds_dwordx4 v[212:213], off
	s_add_i32 m0, s28, 0x2000
	v_lshl_add_u64 v[248:249], s[44:45], 0, v[128:129]
	global_load_lds_dwordx4 v[242:243], off
	s_mov_b32 m0, s63
	v_lshl_add_u64 v[250:251], s[44:45], 0, v[132:133]
	global_load_lds_dwordx4 v[248:249], off
	s_mov_b32 m0, s64
	s_nop 0
	global_load_lds_dwordx4 v[250:251], off
	s_waitcnt vmcnt(8)
	s_waitcnt lgkmcnt(0)
	s_barrier
; #define PG8_STAGE(bufoff, gbase, voff) do { _Pragma("unroll") for (int _i = 0; _i < 2; ++_i) \
;         __builtin_amdgcn_global_load_lds((const unsigned*)((const char*)(gbase) + (voff)[_i]), (PG8_LAS unsigned*)(lds + (bufoff) + ldsw + _i * 8192), 16, 0, 0); } while (0)
; #define PG8_LDA(dst, b, h) do { _Pragma("unroll") for (int m = 0; m < 4; ++m) _Pragma("unroll") for (int k = 0; k < 2; ++k) dst[m][k] = *(const PG8_LAS bf16x8*)(lds + PG8_SA(b, h) + aoff + m * 2048 + k * 1024); } while (0)
; #define PG8_LDB(dst, b, h) do { _Pragma("unroll") for (int n = 0; n < 2; ++n) _Pragma("unroll") for (int k = 0; k < 2; ++k) dst[n][k] = *(const PG8_LAS bf16x8*)(lds + PG8_SB(b, h) + boff + n * 2048 + k * 1024); } while (0)
; #define PG8_MMA(ai, bj, At, Bt) do { __builtin_amdgcn_s_setprio(1); _Pragma("unroll") for (int m = 0; m < 4; ++m) _Pragma("unroll") for (int n = 0; n < 2; ++n) _Pragma("unroll") for (int k = 0; k < 2; ++k) \
;         acc[ai][bj][m][n] = __builtin_amdgcn_mfma_f32_16x16x32_bf16(Bt[n][k], At[m][k], acc[ai][bj][m][n], 0, 0, 0); __builtin_amdgcn_s_setprio(0); } while (0)
; #define PG8_WAIT_V(n) asm volatile("s_waitcnt vmcnt(" #n ")" ::: "memory")
; #define PG8_WAIT_L(n) asm volatile("s_waitcnt lgkmcnt(" #n ")" ::: "memory")
; #define PG8_BAR __builtin_amdgcn_s_barrier()
; #define PG8_SCHED __builtin_amdgcn_sched_barrier(0)
; template <class Epi, class Sched, bool ALIGN_EPI = false, bool SP2 = false>
; __device__ __forceinline__ void gemm_phase(PG8_LAS unsigned char* lds, const Gemm g, const Sched& S, const Epi& E) {
;     ...
;             PG8_WAIT_V(8); PG8_WAIT_L(0); PG8_BAR; PG8_MMA(1, 0, At, B0); PG8_MMA(1, 1, At, B1); PG8_BAR; PG8_SCHED;
;             PG8_LDB(B0, 1, 0); PG8_LDB(B1, 1, 1); PG8_SCHED; PG8_LDA(At, 1, 0); PG8_STAGE(PG8_SA(0, 1), a2 + hstepA, voffA);
;             PG8_WAIT_V(8); PG8_WAIT_L(0); PG8_BAR; PG8_MMA(0, 0, At, B0); PG8_MMA(0, 1, At, B1); PG8_BAR; PG8_SCHED;
	s_setprio 1
	s_waitcnt lgkmcnt(0)
	v_mfma_f32_16x16x32_bf16 v[60:63], v[148:151], v[190:193], v[60:63]
	v_mfma_f32_16x16x32_bf16 v[56:59], v[156:159], v[190:193], v[56:59]
	v_mfma_f32_16x16x32_bf16 v[44:47], v[148:151], v[218:221], v[44:47]
	v_mfma_f32_16x16x32_bf16 v[40:43], v[156:159], v[218:221], v[40:43]
	v_mfma_f32_16x16x32_bf16 v[28:31], v[148:151], v[226:229], v[28:31]
	v_mfma_f32_16x16x32_bf16 v[24:27], v[156:159], v[226:229], v[24:27]
	v_mfma_f32_16x16x32_bf16 v[12:15], v[148:151], v[234:237], v[12:15]
	v_mfma_f32_16x16x32_bf16 v[8:11], v[156:159], v[234:237], v[8:11]
	v_mfma_f32_16x16x32_bf16 v[60:63], v[152:155], v[194:197], v[60:63]
	v_mfma_f32_16x16x32_bf16 v[56:59], v[160:163], v[194:197], v[56:59]
	v_mfma_f32_16x16x32_bf16 v[44:47], v[152:155], v[222:225], v[44:47]
	v_mfma_f32_16x16x32_bf16 v[40:43], v[160:163], v[222:225], v[40:43]
	v_mfma_f32_16x16x32_bf16 v[28:31], v[152:155], v[230:233], v[28:31]
	v_mfma_f32_16x16x32_bf16 v[24:27], v[160:163], v[230:233], v[24:27]
	v_mfma_f32_16x16x32_bf16 v[12:15], v[152:155], v[238:241], v[12:15]
	v_mfma_f32_16x16x32_bf16 v[8:11], v[160:163], v[238:241], v[8:11]
	v_mfma_f32_16x16x32_bf16 v[52:55], v[164:167], v[190:193], v[52:55]
	v_mfma_f32_16x16x32_bf16 v[48:51], v[182:185], v[190:193], v[48:51]
	v_mfma_f32_16x16x32_bf16 v[36:39], v[164:167], v[218:221], v[36:39]
	v_mfma_f32_16x16x32_bf16 v[32:35], v[182:185], v[218:221], v[32:35]
	v_mfma_f32_16x16x32_bf16 v[20:23], v[164:167], v[226:229], v[20:23]
	v_mfma_f32_16x16x32_bf16 v[16:19], v[182:185], v[226:229], v[16:19]
	v_mfma_f32_16x16x32_bf16 v[4:7], v[164:167], v[234:237], v[4:7]
	v_mfma_f32_16x16x32_bf16 v[0:3], v[182:185], v[234:237], v[0:3]
	v_mfma_f32_16x16x32_bf16 v[52:55], v[172:175], v[194:197], v[52:55]
	v_mfma_f32_16x16x32_bf16 v[48:51], v[186:189], v[194:197], v[48:51]
	v_mfma_f32_16x16x32_bf16 v[36:39], v[172:175], v[222:225], v[36:39]
	v_mfma_f32_16x16x32_bf16 v[32:35], v[186:189], v[222:225], v[32:35]
	v_mfma_f32_16x16x32_bf16 v[20:23], v[172:175], v[230:233], v[20:23]
	v_mfma_f32_16x16x32_bf16 v[16:19], v[186:189], v[230:233], v[16:19]
	v_mfma_f32_16x16x32_bf16 v[4:7], v[172:175], v[238:241], v[4:7]
	v_mfma_f32_16x16x32_bf16 v[0:3], v[186:189], v[238:241], v[0:3]
	s_setprio 0
	s_barrier
	s_add_i32 s28, 0, 0x18000
	s_add_i32 s34, 0, 0x1c000
	v_add_u32_e32 v160, s28, v179
	v_add_u32_e32 v168, s34, v179
	ds_read_b128 v[148:151], v160
	ds_read_b128 v[152:155], v160 offset:1024
	ds_read_b128 v[156:159], v160 offset:2048
	ds_read_b128 v[160:163], v160 offset:3072
	ds_read_b128 v[164:167], v168
	ds_read_b128 v[172:175], v168 offset:1024
	ds_read_b128 v[182:185], v168 offset:2048
	ds_read_b128 v[186:189], v168 offset:3072
	s_add_u32 s44, s44, s4
	s_addc_u32 s45, s45, 0
	s_mov_b32 m0, s65
	v_lshl_add_u64 v[198:199], s[44:45], 0, v[128:129]
	ds_read_b128 v[190:193], v180 offset:32768
	ds_read_b128 v[194:197], v180 offset:33792
	ds_read_b128 v[218:221], v180 offset:34816
	ds_read_b128 v[222:225], v180 offset:35840
	ds_read_b128 v[226:229], v180 offset:36864
	ds_read_b128 v[230:233], v180 offset:37888
	ds_read_b128 v[234:237], v180 offset:38912
	ds_read_b128 v[238:241], v180 offset:39936
	global_load_lds_dwordx4 v[198:199], off
	v_lshl_add_u64 v[198:199], s[44:45], 0, v[132:133]
	s_mov_b32 m0, s66
	s_nop 0
	global_load_lds_dwordx4 v[198:199], off
	s_waitcnt vmcnt(8)
	s_waitcnt lgkmcnt(0)
	s_barrier
	s_setprio 1
	s_waitcnt lgkmcnt(0)
	v_mfma_f32_16x16x32_bf16 v[124:127], v[148:151], v[190:193], v[124:127]
	v_mfma_f32_16x16x32_bf16 v[120:123], v[156:159], v[190:193], v[120:123]
	v_mfma_f32_16x16x32_bf16 v[108:111], v[148:151], v[218:221], v[108:111]
	v_mfma_f32_16x16x32_bf16 v[104:107], v[156:159], v[218:221], v[104:107]
	v_mfma_f32_16x16x32_bf16 v[92:95], v[148:151], v[226:229], v[92:95]
	v_mfma_f32_16x16x32_bf16 v[88:91], v[156:159], v[226:229], v[88:91]
	v_mfma_f32_16x16x32_bf16 v[76:79], v[148:151], v[234:237], v[76:79]
	v_mfma_f32_16x16x32_bf16 v[72:75], v[156:159], v[234:237], v[72:75]
	v_mfma_f32_16x16x32_bf16 v[124:127], v[152:155], v[194:197], v[124:127]
	v_mfma_f32_16x16x32_bf16 v[120:123], v[160:163], v[194:197], v[120:123]
	v_mfma_f32_16x16x32_bf16 v[108:111], v[152:155], v[222:225], v[108:111]
	v_mfma_f32_16x16x32_bf16 v[104:107], v[160:163], v[222:225], v[104:107]
	v_mfma_f32_16x16x32_bf16 v[92:95], v[152:155], v[230:233], v[92:95]
	v_mfma_f32_16x16x32_bf16 v[88:91], v[160:163], v[230:233], v[88:91]
	v_mfma_f32_16x16x32_bf16 v[76:79], v[152:155], v[238:241], v[76:79]
	v_mfma_f32_16x16x32_bf16 v[72:75], v[160:163], v[238:241], v[72:75]
	v_mfma_f32_16x16x32_bf16 v[116:119], v[164:167], v[190:193], v[116:119]
	v_mfma_f32_16x16x32_bf16 v[112:115], v[182:185], v[190:193], v[112:115]
	v_mfma_f32_16x16x32_bf16 v[100:103], v[164:167], v[218:221], v[100:103]
	v_mfma_f32_16x16x32_bf16 v[96:99], v[182:185], v[218:221], v[96:99]
	v_mfma_f32_16x16x32_bf16 v[84:87], v[164:167], v[226:229], v[84:87]
	v_mfma_f32_16x16x32_bf16 v[80:83], v[182:185], v[226:229], v[80:83]
	v_mfma_f32_16x16x32_bf16 v[68:71], v[164:167], v[234:237], v[68:71]
	v_mfma_f32_16x16x32_bf16 v[64:67], v[182:185], v[234:237], v[64:67]
	v_mfma_f32_16x16x32_bf16 v[116:119], v[172:175], v[194:197], v[116:119]
	v_mfma_f32_16x16x32_bf16 v[112:115], v[186:189], v[194:197], v[112:115]
	v_mfma_f32_16x16x32_bf16 v[100:103], v[172:175], v[222:225], v[100:103]
	v_mfma_f32_16x16x32_bf16 v[96:99], v[186:189], v[222:225], v[96:99]
	v_mfma_f32_16x16x32_bf16 v[84:87], v[172:175], v[230:233], v[84:87]
	v_mfma_f32_16x16x32_bf16 v[80:83], v[186:189], v[230:233], v[80:83]
	v_mfma_f32_16x16x32_bf16 v[68:71], v[172:175], v[238:241], v[68:71]
	v_mfma_f32_16x16x32_bf16 v[64:67], v[186:189], v[238:241], v[64:67]
	s_setprio 0
	s_barrier
; #define PG8_STAGE(bufoff, gbase, voff) do { _Pragma("unroll") for (int _i = 0; _i < 2; ++_i) \
;         __builtin_amdgcn_global_load_lds((const unsigned*)((const char*)(gbase) + (voff)[_i]), (PG8_LAS unsigned*)(lds + (bufoff) + ldsw + _i * 8192), 16, 0, 0); } while (0)
; #define PG8_LDA(dst, b, h) do { _Pragma("unroll") for (int m = 0; m < 4; ++m) _Pragma("unroll") for (int k = 0; k < 2; ++k) dst[m][k] = *(const PG8_LAS bf16x8*)(lds + PG8_SA(b, h) + aoff + m * 2048 + k * 1024); } while (0)
; #define PG8_MMA(ai, bj, At, Bt) do { __builtin_amdgcn_s_setprio(1); _Pragma("unroll") for (int m = 0; m < 4; ++m) _Pragma("unroll") for (int n = 0; n < 2; ++n) _Pragma("unroll") for (int k = 0; k < 2; ++k) \
;         acc[ai][bj][m][n] = __builtin_amdgcn_mfma_f32_16x16x32_bf16(Bt[n][k], At[m][k], acc[ai][bj][m][n], 0, 0, 0); __builtin_amdgcn_s_setprio(0); } while (0)
; #define PG8_WAIT_V(n) asm volatile("s_waitcnt vmcnt(" #n ")" ::: "memory")
; #define PG8_WAIT_L(n) asm volatile("s_waitcnt lgkmcnt(" #n ")" ::: "memory")
; #define PG8_BAR __builtin_amdgcn_s_barrier()
; #define PG8_SCHED __builtin_amdgcn_sched_barrier(0)
; template <class Epi, class Sched, bool ALIGN_EPI = false, bool SP2 = false>
; __device__ __forceinline__ void gemm_phase(PG8_LAS unsigned char* lds, const Gemm g, const Sched& S, const Epi& E) {
;     ...
;         for (int t = 0; t < nt; t += 2) {
;     ...
;             PG8_LDA(At, 1, 1); PG8_STAGE(PG8_SB(1, 0), b3, voffB); PG8_STAGE(PG8_SB(1, 1), b3 + hstep, voffB); PG8_STAGE(PG8_SA(1, 0), a3, voffA);
;             PG8_WAIT_V(8); PG8_WAIT_L(0); PG8_BAR; PG8_MMA(1, 0, At, B0); PG8_MMA(1, 1, At, B1); PG8_BAR; PG8_SCHED;
	s_add_i32 s28, s28, s62
	v_lshl_add_u64 v[176:177], v[176:177], 0, s[10:11]
	s_mov_b32 m0, s28
	ds_read_b128 v[190:193], v180 offset:49152
	ds_read_b128 v[194:197], v180 offset:50176
	ds_read_b128 v[218:221], v180 offset:51200
	ds_read_b128 v[222:225], v180 offset:52224
	ds_read_b128 v[226:229], v180 offset:53248
	ds_read_b128 v[230:233], v180 offset:54272
	ds_read_b128 v[234:237], v180 offset:55296
	ds_read_b128 v[238:241], v180 offset:56320
	global_load_lds_dwordx4 v[176:177], off
	v_lshl_add_u64 v[176:177], v[210:211], 0, s[10:11]
	s_add_i32 m0, s28, 0x2000
	s_add_i32 s28, s34, s62
	global_load_lds_dwordx4 v[176:177], off
	v_lshl_add_u64 v[176:177], v[212:213], 0, s[10:11]
	s_mov_b32 m0, s28
	s_nop 0
	global_load_lds_dwordx4 v[176:177], off
	v_lshl_add_u64 v[176:177], v[242:243], 0, s[10:11]
	s_add_i32 m0, s28, 0x2000
	s_nop 0
	global_load_lds_dwordx4 v[176:177], off
	v_lshl_add_u64 v[176:177], v[248:249], 0, s[10:11]
	s_mov_b32 m0, s67
	s_nop 0
	global_load_lds_dwordx4 v[176:177], off
	v_lshl_add_u64 v[176:177], v[250:251], 0, s[10:11]
	s_mov_b32 m0, s68
	s_nop 0
	global_load_lds_dwordx4 v[176:177], off
	s_waitcnt vmcnt(8)
	s_waitcnt lgkmcnt(0)
	s_barrier
	s_setprio 1
	s_waitcnt lgkmcnt(0)
	v_mfma_f32_16x16x32_bf16 v[60:63], v[148:151], v[190:193], v[60:63]
	v_mfma_f32_16x16x32_bf16 v[56:59], v[156:159], v[190:193], v[56:59]
	v_mfma_f32_16x16x32_bf16 v[44:47], v[148:151], v[218:221], v[44:47]
	v_mfma_f32_16x16x32_bf16 v[40:43], v[156:159], v[218:221], v[40:43]
	v_mfma_f32_16x16x32_bf16 v[28:31], v[148:151], v[226:229], v[28:31]
	v_mfma_f32_16x16x32_bf16 v[24:27], v[156:159], v[226:229], v[24:27]
	v_mfma_f32_16x16x32_bf16 v[12:15], v[148:151], v[234:237], v[12:15]
	v_mfma_f32_16x16x32_bf16 v[8:11], v[156:159], v[234:237], v[8:11]
	v_mfma_f32_16x16x32_bf16 v[60:63], v[152:155], v[194:197], v[60:63]
	v_mfma_f32_16x16x32_bf16 v[56:59], v[160:163], v[194:197], v[56:59]
	v_mfma_f32_16x16x32_bf16 v[44:47], v[152:155], v[222:225], v[44:47]
	v_mfma_f32_16x16x32_bf16 v[40:43], v[160:163], v[222:225], v[40:43]
	v_mfma_f32_16x16x32_bf16 v[28:31], v[152:155], v[230:233], v[28:31]
	v_mfma_f32_16x16x32_bf16 v[24:27], v[160:163], v[230:233], v[24:27]
	v_mfma_f32_16x16x32_bf16 v[12:15], v[152:155], v[238:241], v[12:15]
	v_mfma_f32_16x16x32_bf16 v[8:11], v[160:163], v[238:241], v[8:11]
	v_mfma_f32_16x16x32_bf16 v[52:55], v[164:167], v[190:193], v[52:55]
	v_mfma_f32_16x16x32_bf16 v[48:51], v[182:185], v[190:193], v[48:51]
	v_mfma_f32_16x16x32_bf16 v[36:39], v[164:167], v[218:221], v[36:39]
	v_mfma_f32_16x16x32_bf16 v[32:35], v[182:185], v[218:221], v[32:35]
	v_mfma_f32_16x16x32_bf16 v[20:23], v[164:167], v[226:229], v[20:23]
	v_mfma_f32_16x16x32_bf16 v[16:19], v[182:185], v[226:229], v[16:19]
	v_mfma_f32_16x16x32_bf16 v[4:7], v[164:167], v[234:237], v[4:7]
	v_mfma_f32_16x16x32_bf16 v[0:3], v[182:185], v[234:237], v[0:3]
	v_mfma_f32_16x16x32_bf16 v[52:55], v[172:175], v[194:197], v[52:55]
	v_mfma_f32_16x16x32_bf16 v[48:51], v[186:189], v[194:197], v[48:51]
	v_mfma_f32_16x16x32_bf16 v[36:39], v[172:175], v[222:225], v[36:39]
	v_mfma_f32_16x16x32_bf16 v[32:35], v[186:189], v[222:225], v[32:35]
	v_mfma_f32_16x16x32_bf16 v[20:23], v[172:175], v[230:233], v[20:23]
	v_mfma_f32_16x16x32_bf16 v[16:19], v[186:189], v[230:233], v[16:19]
	v_mfma_f32_16x16x32_bf16 v[4:7], v[172:175], v[238:241], v[4:7]
	v_mfma_f32_16x16x32_bf16 v[0:3], v[186:189], v[238:241], v[0:3]
	s_setprio 0
	s_barrier
	s_add_u32 s0, s0, 0x100
	s_addc_u32 s1, s1, 0
	s_add_u32 s20, s20, 0x100
	s_addc_u32 s21, s21, 0
	s_cmp_ge_u32 s46, s85
	s_mov_b32 s28, s46
	s_cbranch_scc0 .LBB0_716

; #define PG8_STAGE(bufoff, gbase, voff) do { _Pragma("unroll") for (int _i = 0; _i < 2; ++_i) \
;         __builtin_amdgcn_global_load_lds((const unsigned*)((const char*)(gbase) + (voff)[_i]), (PG8_LAS unsigned*)(lds + (bufoff) + ldsw + _i * 8192), 16, 0, 0); } while (0)
; #define PG8_LDA(dst, b, h) do { _Pragma("unroll") for (int m = 0; m < 4; ++m) _Pragma("unroll") for (int k = 0; k < 2; ++k) dst[m][k] = *(const PG8_LAS bf16x8*)(lds + PG8_SA(b, h) + aoff + m * 2048 + k * 1024); } while (0)
; #define PG8_LDB(dst, b, h) do { _Pragma("unroll") for (int n = 0; n < 2; ++n) _Pragma("unroll") for (int k = 0; k < 2; ++k) dst[n][k] = *(const PG8_LAS bf16x8*)(lds + PG8_SB(b, h) + boff + n * 2048 + k * 1024); } while (0)
; #define PG8_MMA(ai, bj, At, Bt) do { __builtin_amdgcn_s_setprio(1); _Pragma("unroll") for (int m = 0; m < 4; ++m) _Pragma("unroll") for (int n = 0; n < 2; ++n) _Pragma("unroll") for (int k = 0; k < 2; ++k) \
;         acc[ai][bj][m][n] = __builtin_amdgcn_mfma_f32_16x16x32_bf16(Bt[n][k], At[m][k], acc[ai][bj][m][n], 0, 0, 0); __builtin_amdgcn_s_setprio(0); } while (0)
; #define PG8_WAIT_V(n) asm volatile("s_waitcnt vmcnt(" #n ")" ::: "memory")
; #define PG8_BAR __builtin_amdgcn_s_barrier()
; template <class Epi, class Sched, bool ALIGN_EPI = false, bool SP2 = false>
; __device__ __forceinline__ void gemm_phase(PG8_LAS unsigned char* lds, const Gemm g, const Sched& S, const Epi& E) {
;     ...
;         for (int t = 0; t < nt; t += 2) {
;             const bool last = (t == nt - 2);
;             const char* a1 = cA + (size_t)(t + 1) * kstep;
;             const char* a2 = last ? nA : cA + (size_t)(t + 2) * kstep; const char* b2 = last ? nB : cB + (size_t)(t + 2) * kstep;
;             const char* a3 = a2 + kstep; const char* b3 = b2 + kstep;
;             if (last && has_next) S.a_ready(nxt);
;             if constexpr (SP2) {
;             PG8_LDB(B0, 0, 0); PG8_LDB(B1, 0, 1); PG8_SCHED; PG8_LDA(At, 0, 0); PG8_STAGE(PG8_SA(1, 1), a1 + hstepA, voffA);
;             PG8_WAIT_V(8); PG8_WAIT_L(0); PG8_BAR; PG8_MMA(0, 0, At, B0); PG8_MMA(0, 1, At, B1); PG8_BAR; PG8_SCHED;
;             PG8_LDA(At, 0, 1); PG8_STAGE(PG8_SB(0, 0), b2, voffB); PG8_STAGE(PG8_SB(0, 1), b2 + hstep, voffB); PG8_STAGE(PG8_SA(0, 0), a2, voffA);
;             PG8_WAIT_V(8); PG8_WAIT_L(0); PG8_BAR; PG8_MMA(1, 0, At, B0); PG8_MMA(1, 1, At, B1); PG8_BAR; PG8_SCHED;
.LBB0_1049:
	s_add_i32 s59, s44, 2
	s_add_u32 vcc_lo, s42, 0x80
	s_addc_u32 s45, s43, 0
	s_add_i32 s34, 0, 0x10000
	s_cmp_eq_u32 s86, s44
	s_cselect_b32 s45, s1, s45
	s_cselect_b32 s44, s0, vcc_lo
	v_add_u32_e32 v146, s34, v149
	s_cselect_b32 vcc_hi, s83, s58
	s_cselect_b32 vcc_lo, s82, s57
	s_add_i32 s35, 0, 0x14000
	ds_read_b128 v[128:131], v146
	ds_read_b128 v[142:145], v146 offset:1024
	ds_read_b128 v[152:155], v146 offset:2048
	ds_read_b128 v[156:159], v146 offset:3072
	v_add_u32_e32 v146, s35, v149
	ds_read_b128 v[160:163], v146
	ds_read_b128 v[164:167], v146 offset:1024
	ds_read_b128 v[172:175], v146 offset:2048
	ds_read_b128 v[176:179], v146 offset:3072
	v_lshl_add_u64 v[146:147], s[42:43], 0, v[138:139]
	s_add_i32 m0, s62, 0xc000
	ds_read_b128 v[180:183], v151
	ds_read_b128 v[184:187], v151 offset:1024
	ds_read_b128 v[188:191], v151 offset:2048
	ds_read_b128 v[192:195], v151 offset:3072
	ds_read_b128 v[218:221], v151 offset:4096
	ds_read_b128 v[222:225], v151 offset:5120
	ds_read_b128 v[226:229], v151 offset:6144
	ds_read_b128 v[230:233], v151 offset:7168
	global_load_lds_dwordx4 v[146:147], off
	v_lshl_add_u64 v[146:147], s[42:43], 0, v[140:141]
	s_add_i32 m0, s62, 0xe000
	s_nop 0
	global_load_lds_dwordx4 v[146:147], off
	s_waitcnt vmcnt(8)
	s_waitcnt lgkmcnt(0)
	s_barrier
	s_setprio 1
	s_waitcnt lgkmcnt(0)
	v_mfma_f32_16x16x32_bf16 v[120:123], v[128:131], v[180:183], v[120:123]
	v_mfma_f32_16x16x32_bf16 v[124:127], v[152:155], v[180:183], v[124:127]
	v_mfma_f32_16x16x32_bf16 v[108:111], v[128:131], v[188:191], v[108:111]
	v_mfma_f32_16x16x32_bf16 v[104:107], v[152:155], v[188:191], v[104:107]
	v_mfma_f32_16x16x32_bf16 v[92:95], v[128:131], v[218:221], v[92:95]
	v_mfma_f32_16x16x32_bf16 v[88:91], v[152:155], v[218:221], v[88:91]
	v_mfma_f32_16x16x32_bf16 v[76:79], v[128:131], v[226:229], v[76:79]
	v_mfma_f32_16x16x32_bf16 v[72:75], v[152:155], v[226:229], v[72:75]
	v_mfma_f32_16x16x32_bf16 v[120:123], v[142:145], v[184:187], v[120:123]
	v_mfma_f32_16x16x32_bf16 v[124:127], v[156:159], v[184:187], v[124:127]
	v_mfma_f32_16x16x32_bf16 v[108:111], v[142:145], v[192:195], v[108:111]
	v_mfma_f32_16x16x32_bf16 v[104:107], v[156:159], v[192:195], v[104:107]
	v_mfma_f32_16x16x32_bf16 v[92:95], v[142:145], v[222:225], v[92:95]
	v_mfma_f32_16x16x32_bf16 v[88:91], v[156:159], v[222:225], v[88:91]
	v_mfma_f32_16x16x32_bf16 v[76:79], v[142:145], v[230:233], v[76:79]
	v_mfma_f32_16x16x32_bf16 v[72:75], v[156:159], v[230:233], v[72:75]
	v_mfma_f32_16x16x32_bf16 v[116:119], v[160:163], v[180:183], v[116:119]
	v_mfma_f32_16x16x32_bf16 v[112:115], v[172:175], v[180:183], v[112:115]
	v_mfma_f32_16x16x32_bf16 v[100:103], v[160:163], v[188:191], v[100:103]
	v_mfma_f32_16x16x32_bf16 v[96:99], v[172:175], v[188:191], v[96:99]
	v_mfma_f32_16x16x32_bf16 v[84:87], v[160:163], v[218:221], v[84:87]
	v_mfma_f32_16x16x32_bf16 v[80:83], v[172:175], v[218:221], v[80:83]
	v_mfma_f32_16x16x32_bf16 v[68:71], v[160:163], v[226:229], v[68:71]
	v_mfma_f32_16x16x32_bf16 v[64:67], v[172:175], v[226:229], v[64:67]
	v_mfma_f32_16x16x32_bf16 v[116:119], v[164:167], v[184:187], v[116:119]
	v_mfma_f32_16x16x32_bf16 v[112:115], v[176:179], v[184:187], v[112:115]
	v_mfma_f32_16x16x32_bf16 v[100:103], v[164:167], v[192:195], v[100:103]
	v_mfma_f32_16x16x32_bf16 v[96:99], v[176:179], v[192:195], v[96:99]
	v_mfma_f32_16x16x32_bf16 v[84:87], v[164:167], v[222:225], v[84:87]
	v_mfma_f32_16x16x32_bf16 v[80:83], v[176:179], v[222:225], v[80:83]
	v_mfma_f32_16x16x32_bf16 v[68:71], v[164:167], v[230:233], v[68:71]
	v_mfma_f32_16x16x32_bf16 v[64:67], v[176:179], v[230:233], v[64:67]
	s_setprio 0
	s_barrier
	s_add_i32 s34, s34, s61
	v_lshl_add_u64 v[146:147], vcc, 0, v[168:169]
	s_mov_b32 m0, s34
	ds_read_b128 v[180:183], v151 offset:16384
	ds_read_b128 v[184:187], v151 offset:17408
	ds_read_b128 v[188:191], v151 offset:18432
	ds_read_b128 v[192:195], v151 offset:19456
	ds_read_b128 v[218:221], v151 offset:20480
	ds_read_b128 v[222:225], v151 offset:21504
	ds_read_b128 v[226:229], v151 offset:22528
	ds_read_b128 v[230:233], v151 offset:23552
	global_load_lds_dwordx4 v[146:147], off
	s_add_i32 m0, s34, 0x2000
	v_lshl_add_u64 v[196:197], vcc, 0, v[136:137]
	s_add_u32 vcc_lo, vcc_lo, s2
	s_addc_u32 vcc_hi, vcc_hi, 0
	s_add_i32 s34, s35, s61
	global_load_lds_dwordx4 v[196:197], off
	v_lshl_add_u64 v[210:211], vcc, 0, v[168:169]
	s_mov_b32 m0, s34
	v_lshl_add_u64 v[212:213], vcc, 0, v[136:137]
	global_load_lds_dwordx4 v[210:211], off
	s_add_i32 m0, s34, 0x2000
	v_lshl_add_u64 v[234:235], s[44:45], 0, v[132:133]
	global_load_lds_dwordx4 v[212:213], off
	s_mov_b32 m0, s62
	v_lshl_add_u64 v[236:237], s[44:45], 0, v[134:135]
	global_load_lds_dwordx4 v[234:235], off
	s_mov_b32 m0, s63
	s_nop 0
	global_load_lds_dwordx4 v[236:237], off
	s_waitcnt vmcnt(8)
	s_waitcnt lgkmcnt(0)
	s_barrier
; #define PG8_STAGE(bufoff, gbase, voff) do { _Pragma("unroll") for (int _i = 0; _i < 2; ++_i) \
;         __builtin_amdgcn_global_load_lds((const unsigned*)((const char*)(gbase) + (voff)[_i]), (PG8_LAS unsigned*)(lds + (bufoff) + ldsw + _i * 8192), 16, 0, 0); } while (0)
; #define PG8_LDA(dst, b, h) do { _Pragma("unroll") for (int m = 0; m < 4; ++m) _Pragma("unroll") for (int k = 0; k < 2; ++k) dst[m][k] = *(const PG8_LAS bf16x8*)(lds + PG8_SA(b, h) + aoff + m * 2048 + k * 1024); } while (0)
; #define PG8_LDB(dst, b, h) do { _Pragma("unroll") for (int n = 0; n < 2; ++n) _Pragma("unroll") for (int k = 0; k < 2; ++k) dst[n][k] = *(const PG8_LAS bf16x8*)(lds + PG8_SB(b, h) + boff + n * 2048 + k * 1024); } while (0)
; #define PG8_MMA(ai, bj, At, Bt) do { __builtin_amdgcn_s_setprio(1); _Pragma("unroll") for (int m = 0; m < 4; ++m) _Pragma("unroll") for (int n = 0; n < 2; ++n) _Pragma("unroll") for (int k = 0; k < 2; ++k) \
;         acc[ai][bj][m][n] = __builtin_amdgcn_mfma_f32_16x16x32_bf16(Bt[n][k], At[m][k], acc[ai][bj][m][n], 0, 0, 0); __builtin_amdgcn_s_setprio(0); } while (0)
; #define PG8_WAIT_V(n) asm volatile("s_waitcnt vmcnt(" #n ")" ::: "memory")
; #define PG8_WAIT_L(n) asm volatile("s_waitcnt lgkmcnt(" #n ")" ::: "memory")
; #define PG8_BAR __builtin_amdgcn_s_barrier()
; #define PG8_SCHED __builtin_amdgcn_sched_barrier(0)
; template <class Epi, class Sched, bool ALIGN_EPI = false, bool SP2 = false>
; __device__ __forceinline__ void gemm_phase(PG8_LAS unsigned char* lds, const Gemm g, const Sched& S, const Epi& E) {
;     ...
;             PG8_WAIT_V(8); PG8_WAIT_L(0); PG8_BAR; PG8_MMA(1, 0, At, B0); PG8_MMA(1, 1, At, B1); PG8_BAR; PG8_SCHED;
;             PG8_LDB(B0, 1, 0); PG8_LDB(B1, 1, 1); PG8_SCHED; PG8_LDA(At, 1, 0); PG8_STAGE(PG8_SA(0, 1), a2 + hstepA, voffA);
;             PG8_WAIT_V(8); PG8_WAIT_L(0); PG8_BAR; PG8_MMA(0, 0, At, B0); PG8_MMA(0, 1, At, B1); PG8_BAR; PG8_SCHED;
	s_setprio 1
	s_waitcnt lgkmcnt(0)
	v_mfma_f32_16x16x32_bf16 v[60:63], v[128:131], v[180:183], v[60:63]
	v_mfma_f32_16x16x32_bf16 v[56:59], v[152:155], v[180:183], v[56:59]
	v_mfma_f32_16x16x32_bf16 v[44:47], v[128:131], v[188:191], v[44:47]
	v_mfma_f32_16x16x32_bf16 v[40:43], v[152:155], v[188:191], v[40:43]
	v_mfma_f32_16x16x32_bf16 v[28:31], v[128:131], v[218:221], v[28:31]
	v_mfma_f32_16x16x32_bf16 v[24:27], v[152:155], v[218:221], v[24:27]
	v_mfma_f32_16x16x32_bf16 v[12:15], v[128:131], v[226:229], v[12:15]
	v_mfma_f32_16x16x32_bf16 v[8:11], v[152:155], v[226:229], v[8:11]
	v_mfma_f32_16x16x32_bf16 v[60:63], v[142:145], v[184:187], v[60:63]
	v_mfma_f32_16x16x32_bf16 v[56:59], v[156:159], v[184:187], v[56:59]
	v_mfma_f32_16x16x32_bf16 v[44:47], v[142:145], v[192:195], v[44:47]
	v_mfma_f32_16x16x32_bf16 v[40:43], v[156:159], v[192:195], v[40:43]
	v_mfma_f32_16x16x32_bf16 v[28:31], v[142:145], v[222:225], v[28:31]
	v_mfma_f32_16x16x32_bf16 v[24:27], v[156:159], v[222:225], v[24:27]
	v_mfma_f32_16x16x32_bf16 v[12:15], v[142:145], v[230:233], v[12:15]
	v_mfma_f32_16x16x32_bf16 v[8:11], v[156:159], v[230:233], v[8:11]
	v_mfma_f32_16x16x32_bf16 v[52:55], v[160:163], v[180:183], v[52:55]
	v_mfma_f32_16x16x32_bf16 v[48:51], v[172:175], v[180:183], v[48:51]
	v_mfma_f32_16x16x32_bf16 v[36:39], v[160:163], v[188:191], v[36:39]
	v_mfma_f32_16x16x32_bf16 v[32:35], v[172:175], v[188:191], v[32:35]
	v_mfma_f32_16x16x32_bf16 v[20:23], v[160:163], v[218:221], v[20:23]
	v_mfma_f32_16x16x32_bf16 v[16:19], v[172:175], v[218:221], v[16:19]
	v_mfma_f32_16x16x32_bf16 v[4:7], v[160:163], v[226:229], v[4:7]
	v_mfma_f32_16x16x32_bf16 v[0:3], v[172:175], v[226:229], v[0:3]
	v_mfma_f32_16x16x32_bf16 v[52:55], v[164:167], v[184:187], v[52:55]
	v_mfma_f32_16x16x32_bf16 v[48:51], v[176:179], v[184:187], v[48:51]
	v_mfma_f32_16x16x32_bf16 v[36:39], v[164:167], v[192:195], v[36:39]
	v_mfma_f32_16x16x32_bf16 v[32:35], v[176:179], v[192:195], v[32:35]
	v_mfma_f32_16x16x32_bf16 v[20:23], v[164:167], v[222:225], v[20:23]
	v_mfma_f32_16x16x32_bf16 v[16:19], v[176:179], v[222:225], v[16:19]
	v_mfma_f32_16x16x32_bf16 v[4:7], v[164:167], v[230:233], v[4:7]
	v_mfma_f32_16x16x32_bf16 v[0:3], v[176:179], v[230:233], v[0:3]
	s_setprio 0
	s_barrier
	s_add_i32 s34, 0, 0x18000
	s_add_i32 s35, 0, 0x1c000
	v_add_u32_e32 v156, s34, v149
	v_add_u32_e32 v176, s35, v149
	ds_read_b128 v[128:131], v156
	ds_read_b128 v[142:145], v156 offset:1024
	ds_read_b128 v[152:155], v156 offset:2048
	ds_read_b128 v[156:159], v156 offset:3072
	ds_read_b128 v[160:163], v176
	ds_read_b128 v[164:167], v176 offset:1024
	ds_read_b128 v[172:175], v176 offset:2048
	ds_read_b128 v[176:179], v176 offset:3072
	s_add_u32 s44, s44, s22
	s_addc_u32 s45, s45, 0
	s_mov_b32 m0, s64
	v_lshl_add_u64 v[238:239], s[44:45], 0, v[132:133]
	ds_read_b128 v[180:183], v151 offset:32768
	ds_read_b128 v[184:187], v151 offset:33792
	ds_read_b128 v[188:191], v151 offset:34816
	ds_read_b128 v[192:195], v151 offset:35840
	ds_read_b128 v[218:221], v151 offset:36864
	ds_read_b128 v[222:225], v151 offset:37888
	ds_read_b128 v[226:229], v151 offset:38912
	ds_read_b128 v[230:233], v151 offset:39936
	global_load_lds_dwordx4 v[238:239], off
	v_lshl_add_u64 v[238:239], s[44:45], 0, v[134:135]
	s_mov_b32 m0, s65
	s_nop 0
	global_load_lds_dwordx4 v[238:239], off
	s_waitcnt vmcnt(8)
	s_waitcnt lgkmcnt(0)
	s_barrier
	s_setprio 1
	s_waitcnt lgkmcnt(0)
	v_mfma_f32_16x16x32_bf16 v[120:123], v[128:131], v[180:183], v[120:123]
	v_mfma_f32_16x16x32_bf16 v[124:127], v[152:155], v[180:183], v[124:127]
	v_mfma_f32_16x16x32_bf16 v[108:111], v[128:131], v[188:191], v[108:111]
	v_mfma_f32_16x16x32_bf16 v[104:107], v[152:155], v[188:191], v[104:107]
	v_mfma_f32_16x16x32_bf16 v[92:95], v[128:131], v[218:221], v[92:95]
	v_mfma_f32_16x16x32_bf16 v[88:91], v[152:155], v[218:221], v[88:91]
	v_mfma_f32_16x16x32_bf16 v[76:79], v[128:131], v[226:229], v[76:79]
	v_mfma_f32_16x16x32_bf16 v[72:75], v[152:155], v[226:229], v[72:75]
	v_mfma_f32_16x16x32_bf16 v[120:123], v[142:145], v[184:187], v[120:123]
	v_mfma_f32_16x16x32_bf16 v[124:127], v[156:159], v[184:187], v[124:127]
	v_mfma_f32_16x16x32_bf16 v[108:111], v[142:145], v[192:195], v[108:111]
	v_mfma_f32_16x16x32_bf16 v[104:107], v[156:159], v[192:195], v[104:107]
	v_mfma_f32_16x16x32_bf16 v[92:95], v[142:145], v[222:225], v[92:95]
	v_mfma_f32_16x16x32_bf16 v[88:91], v[156:159], v[222:225], v[88:91]
	v_mfma_f32_16x16x32_bf16 v[76:79], v[142:145], v[230:233], v[76:79]
	v_mfma_f32_16x16x32_bf16 v[72:75], v[156:159], v[230:233], v[72:75]
	v_mfma_f32_16x16x32_bf16 v[116:119], v[160:163], v[180:183], v[116:119]
	v_mfma_f32_16x16x32_bf16 v[112:115], v[172:175], v[180:183], v[112:115]
	v_mfma_f32_16x16x32_bf16 v[100:103], v[160:163], v[188:191], v[100:103]
	v_mfma_f32_16x16x32_bf16 v[96:99], v[172:175], v[188:191], v[96:99]
	v_mfma_f32_16x16x32_bf16 v[84:87], v[160:163], v[218:221], v[84:87]
	v_mfma_f32_16x16x32_bf16 v[80:83], v[172:175], v[218:221], v[80:83]
	v_mfma_f32_16x16x32_bf16 v[68:71], v[160:163], v[226:229], v[68:71]
	v_mfma_f32_16x16x32_bf16 v[64:67], v[172:175], v[226:229], v[64:67]
	v_mfma_f32_16x16x32_bf16 v[116:119], v[164:167], v[184:187], v[116:119]
	v_mfma_f32_16x16x32_bf16 v[112:115], v[176:179], v[184:187], v[112:115]
	v_mfma_f32_16x16x32_bf16 v[100:103], v[164:167], v[192:195], v[100:103]
	v_mfma_f32_16x16x32_bf16 v[96:99], v[176:179], v[192:195], v[96:99]
	v_mfma_f32_16x16x32_bf16 v[84:87], v[164:167], v[222:225], v[84:87]
	v_mfma_f32_16x16x32_bf16 v[80:83], v[176:179], v[222:225], v[80:83]
	v_mfma_f32_16x16x32_bf16 v[68:71], v[164:167], v[230:233], v[68:71]
	v_mfma_f32_16x16x32_bf16 v[64:67], v[176:179], v[230:233], v[64:67]
	s_setprio 0
	s_barrier
; #define PG8_STAGE(bufoff, gbase, voff) do { _Pragma("unroll") for (int _i = 0; _i < 2; ++_i) \
;         __builtin_amdgcn_global_load_lds((const unsigned*)((const char*)(gbase) + (voff)[_i]), (PG8_LAS unsigned*)(lds + (bufoff) + ldsw + _i * 8192), 16, 0, 0); } while (0)
; #define PG8_LDA(dst, b, h) do { _Pragma("unroll") for (int m = 0; m < 4; ++m) _Pragma("unroll") for (int k = 0; k < 2; ++k) dst[m][k] = *(const PG8_LAS bf16x8*)(lds + PG8_SA(b, h) + aoff + m * 2048 + k * 1024); } while (0)
; #define PG8_MMA(ai, bj, At, Bt) do { __builtin_amdgcn_s_setprio(1); _Pragma("unroll") for (int m = 0; m < 4; ++m) _Pragma("unroll") for (int n = 0; n < 2; ++n) _Pragma("unroll") for (int k = 0; k < 2; ++k) \
;         acc[ai][bj][m][n] = __builtin_amdgcn_mfma_f32_16x16x32_bf16(Bt[n][k], At[m][k], acc[ai][bj][m][n], 0, 0, 0); __builtin_amdgcn_s_setprio(0); } while (0)
; #define PG8_WAIT_V(n) asm volatile("s_waitcnt vmcnt(" #n ")" ::: "memory")
; #define PG8_WAIT_L(n) asm volatile("s_waitcnt lgkmcnt(" #n ")" ::: "memory")
; #define PG8_BAR __builtin_amdgcn_s_barrier()
; #define PG8_SCHED __builtin_amdgcn_sched_barrier(0)
; template <class Epi, class Sched, bool ALIGN_EPI = false, bool SP2 = false>
; __device__ __forceinline__ void gemm_phase(PG8_LAS unsigned char* lds, const Gemm g, const Sched& S, const Epi& E) {
;     ...
;         for (int t = 0; t < nt; t += 2) {
;     ...
;             PG8_LDA(At, 1, 1); PG8_STAGE(PG8_SB(1, 0), b3, voffB); PG8_STAGE(PG8_SB(1, 1), b3 + hstep, voffB); PG8_STAGE(PG8_SA(1, 0), a3, voffA);
;             PG8_WAIT_V(8); PG8_WAIT_L(0); PG8_BAR; PG8_MMA(1, 0, At, B0); PG8_MMA(1, 1, At, B1); PG8_BAR; PG8_SCHED;
	s_add_i32 s34, s34, s61
	v_lshl_add_u64 v[146:147], v[146:147], 0, s[10:11]
	s_mov_b32 m0, s34
	ds_read_b128 v[180:183], v151 offset:49152
	ds_read_b128 v[184:187], v151 offset:50176
	ds_read_b128 v[188:191], v151 offset:51200
	ds_read_b128 v[192:195], v151 offset:52224
	ds_read_b128 v[218:221], v151 offset:53248
	ds_read_b128 v[222:225], v151 offset:54272
	ds_read_b128 v[226:229], v151 offset:55296
	ds_read_b128 v[230:233], v151 offset:56320
	global_load_lds_dwordx4 v[146:147], off
	v_lshl_add_u64 v[146:147], v[196:197], 0, s[10:11]
	s_add_i32 m0, s34, 0x2000
	s_add_i32 s34, s35, s61
	global_load_lds_dwordx4 v[146:147], off
	v_lshl_add_u64 v[146:147], v[210:211], 0, s[10:11]
	s_mov_b32 m0, s34
	s_nop 0
	global_load_lds_dwordx4 v[146:147], off
	v_lshl_add_u64 v[146:147], v[212:213], 0, s[10:11]
	s_add_i32 m0, s34, 0x2000
	s_nop 0
	global_load_lds_dwordx4 v[146:147], off
	v_lshl_add_u64 v[146:147], v[234:235], 0, s[10:11]
	s_mov_b32 m0, s69
	s_nop 0
	global_load_lds_dwordx4 v[146:147], off
	v_lshl_add_u64 v[146:147], v[236:237], 0, s[10:11]
	s_mov_b32 m0, s85
	s_nop 0
	global_load_lds_dwordx4 v[146:147], off
	s_waitcnt vmcnt(8)
	s_waitcnt lgkmcnt(0)
	s_barrier
	s_setprio 1
	s_waitcnt lgkmcnt(0)
	v_mfma_f32_16x16x32_bf16 v[60:63], v[128:131], v[180:183], v[60:63]
	v_mfma_f32_16x16x32_bf16 v[56:59], v[152:155], v[180:183], v[56:59]
	v_mfma_f32_16x16x32_bf16 v[44:47], v[128:131], v[188:191], v[44:47]
	v_mfma_f32_16x16x32_bf16 v[40:43], v[152:155], v[188:191], v[40:43]
	v_mfma_f32_16x16x32_bf16 v[28:31], v[128:131], v[218:221], v[28:31]
	v_mfma_f32_16x16x32_bf16 v[24:27], v[152:155], v[218:221], v[24:27]
	v_mfma_f32_16x16x32_bf16 v[12:15], v[128:131], v[226:229], v[12:15]
	v_mfma_f32_16x16x32_bf16 v[8:11], v[152:155], v[226:229], v[8:11]
	v_mfma_f32_16x16x32_bf16 v[60:63], v[142:145], v[184:187], v[60:63]
	v_mfma_f32_16x16x32_bf16 v[56:59], v[156:159], v[184:187], v[56:59]
	v_mfma_f32_16x16x32_bf16 v[44:47], v[142:145], v[192:195], v[44:47]
	v_mfma_f32_16x16x32_bf16 v[40:43], v[156:159], v[192:195], v[40:43]
	v_mfma_f32_16x16x32_bf16 v[28:31], v[142:145], v[222:225], v[28:31]
	v_mfma_f32_16x16x32_bf16 v[24:27], v[156:159], v[222:225], v[24:27]
	v_mfma_f32_16x16x32_bf16 v[12:15], v[142:145], v[230:233], v[12:15]
	v_mfma_f32_16x16x32_bf16 v[8:11], v[156:159], v[230:233], v[8:11]
	v_mfma_f32_16x16x32_bf16 v[52:55], v[160:163], v[180:183], v[52:55]
	v_mfma_f32_16x16x32_bf16 v[48:51], v[172:175], v[180:183], v[48:51]
	v_mfma_f32_16x16x32_bf16 v[36:39], v[160:163], v[188:191], v[36:39]
	v_mfma_f32_16x16x32_bf16 v[32:35], v[172:175], v[188:191], v[32:35]
	v_mfma_f32_16x16x32_bf16 v[20:23], v[160:163], v[218:221], v[20:23]
	v_mfma_f32_16x16x32_bf16 v[16:19], v[172:175], v[218:221], v[16:19]
	v_mfma_f32_16x16x32_bf16 v[4:7], v[160:163], v[226:229], v[4:7]
	v_mfma_f32_16x16x32_bf16 v[0:3], v[172:175], v[226:229], v[0:3]
	v_mfma_f32_16x16x32_bf16 v[52:55], v[164:167], v[184:187], v[52:55]
	v_mfma_f32_16x16x32_bf16 v[48:51], v[176:179], v[184:187], v[48:51]
	v_mfma_f32_16x16x32_bf16 v[36:39], v[164:167], v[192:195], v[36:39]
	v_mfma_f32_16x16x32_bf16 v[32:35], v[176:179], v[192:195], v[32:35]
	v_mfma_f32_16x16x32_bf16 v[20:23], v[164:167], v[222:225], v[20:23]
	v_mfma_f32_16x16x32_bf16 v[16:19], v[176:179], v[222:225], v[16:19]
	v_mfma_f32_16x16x32_bf16 v[4:7], v[164:167], v[230:233], v[4:7]
	v_mfma_f32_16x16x32_bf16 v[0:3], v[176:179], v[230:233], v[0:3]
	s_setprio 0
	s_barrier
	s_add_u32 s42, s42, 0x100
	s_addc_u32 s43, s43, 0
	s_add_u32 s57, s57, 0x100
	s_addc_u32 s58, s58, 0
	s_cmp_ge_u32 s59, s68
	s_mov_b32 s44, s59
	s_cbranch_scc0 .LBB0_1049

; #define PG8_STAGE(bufoff, gbase, voff) do { _Pragma("unroll") for (int _i = 0; _i < 2; ++_i) \
;         __builtin_amdgcn_global_load_lds((const unsigned*)((const char*)(gbase) + (voff)[_i]), (PG8_LAS unsigned*)(lds + (bufoff) + ldsw + _i * 8192), 16, 0, 0); } while (0)
; #define PG8_LDA(dst, b, h) do { _Pragma("unroll") for (int m = 0; m < 4; ++m) _Pragma("unroll") for (int k = 0; k < 2; ++k) dst[m][k] = *(const PG8_LAS bf16x8*)(lds + PG8_SA(b, h) + aoff + m * 2048 + k * 1024); } while (0)
; #define PG8_LDB(dst, b, h) do { _Pragma("unroll") for (int n = 0; n < 2; ++n) _Pragma("unroll") for (int k = 0; k < 2; ++k) dst[n][k] = *(const PG8_LAS bf16x8*)(lds + PG8_SB(b, h) + boff + n * 2048 + k * 1024); } while (0)
; #define PG8_MMA(ai, bj, At, Bt) do { __builtin_amdgcn_s_setprio(1); _Pragma("unroll") for (int m = 0; m < 4; ++m) _Pragma("unroll") for (int n = 0; n < 2; ++n) _Pragma("unroll") for (int k = 0; k < 2; ++k) \
;         acc[ai][bj][m][n] = __builtin_amdgcn_mfma_f32_16x16x32_bf16(Bt[n][k], At[m][k], acc[ai][bj][m][n], 0, 0, 0); __builtin_amdgcn_s_setprio(0); } while (0)
; #define PG8_WAIT_V(n) asm volatile("s_waitcnt vmcnt(" #n ")" ::: "memory")
; #define PG8_BAR __builtin_amdgcn_s_barrier()
; template <class Epi, class Sched, bool ALIGN_EPI = false, bool SP2 = false>
; __device__ __forceinline__ void gemm_phase(PG8_LAS unsigned char* lds, const Gemm g, const Sched& S, const Epi& E) {
;     ...
;         for (int t = 0; t < nt; t += 2) {
;             const bool last = (t == nt - 2);
;             const char* a1 = cA + (size_t)(t + 1) * kstep;
;             const char* a2 = last ? nA : cA + (size_t)(t + 2) * kstep; const char* b2 = last ? nB : cB + (size_t)(t + 2) * kstep;
;             const char* a3 = a2 + kstep; const char* b3 = b2 + kstep;
;             if (last && has_next) S.a_ready(nxt);
;             if constexpr (SP2) {
;             PG8_LDB(B0, 0, 0); PG8_LDB(B1, 0, 1); PG8_SCHED; PG8_LDA(At, 0, 0); PG8_STAGE(PG8_SA(1, 1), a1 + hstepA, voffA);
;             PG8_WAIT_V(8); PG8_WAIT_L(0); PG8_BAR; PG8_MMA(0, 0, At, B0); PG8_MMA(0, 1, At, B1); PG8_BAR; PG8_SCHED;
;             PG8_LDA(At, 0, 1); PG8_STAGE(PG8_SB(0, 0), b2, voffB); PG8_STAGE(PG8_SB(0, 1), b2 + hstep, voffB); PG8_STAGE(PG8_SA(0, 0), a2, voffA);
;             PG8_WAIT_V(8); PG8_WAIT_L(0); PG8_BAR; PG8_MMA(1, 0, At, B0); PG8_MMA(1, 1, At, B1); PG8_BAR; PG8_SCHED;
.LBB0_1168:
	s_add_i32 s74, s22, 2
	s_add_u32 s75, s4, 0x80
	s_addc_u32 s23, s5, 0
	s_add_i32 s78, 0, 0x10000
	s_cmp_eq_u32 s66, s22
	s_cselect_b32 s23, s1, s23
	s_cselect_b32 s22, s0, s75
	v_add_u32_e32 v144, s78, v146
	s_cselect_b32 s77, s53, s21
	s_cselect_b32 s76, s52, s20
	s_add_i32 s75, 0, 0x14000
	ds_read_b128 v[140:143], v144
	ds_read_b128 v[150:153], v144 offset:1024
	ds_read_b128 v[154:157], v144 offset:2048
	ds_read_b128 v[158:161], v144 offset:3072
	v_add_u32_e32 v144, s75, v146
	ds_read_b128 v[162:165], v144
	ds_read_b128 v[172:175], v144 offset:1024
	ds_read_b128 v[176:179], v144 offset:2048
	ds_read_b128 v[180:183], v144 offset:3072
	v_lshl_add_u64 v[166:167], s[4:5], 0, v[136:137]
	s_add_i32 m0, s59, 0xc000
	ds_read_b128 v[184:187], v148
	ds_read_b128 v[188:191], v148 offset:1024
	ds_read_b128 v[192:195], v148 offset:2048
	ds_read_b128 v[218:221], v148 offset:3072
	ds_read_b128 v[222:225], v148 offset:4096
	ds_read_b128 v[226:229], v148 offset:5120
	ds_read_b128 v[230:233], v148 offset:6144
	ds_read_b128 v[234:237], v148 offset:7168
	global_load_lds_dwordx4 v[166:167], off
	v_lshl_add_u64 v[166:167], s[4:5], 0, v[138:139]
	s_add_i32 m0, s59, 0xe000
	s_nop 0
	global_load_lds_dwordx4 v[166:167], off
	s_waitcnt vmcnt(8)
	s_waitcnt lgkmcnt(0)
	s_barrier
	s_setprio 1
	s_waitcnt lgkmcnt(0)
	v_mfma_f32_16x16x32_bf16 v[120:123], v[140:143], v[184:187], v[120:123]
	v_mfma_f32_16x16x32_bf16 v[112:115], v[154:157], v[184:187], v[112:115]
	v_mfma_f32_16x16x32_bf16 v[104:107], v[140:143], v[192:195], v[104:107]
	v_mfma_f32_16x16x32_bf16 v[96:99], v[154:157], v[192:195], v[96:99]
	v_mfma_f32_16x16x32_bf16 v[88:91], v[140:143], v[222:225], v[88:91]
	v_mfma_f32_16x16x32_bf16 v[80:83], v[154:157], v[222:225], v[80:83]
	v_mfma_f32_16x16x32_bf16 v[72:75], v[140:143], v[230:233], v[72:75]
	v_mfma_f32_16x16x32_bf16 v[64:67], v[154:157], v[230:233], v[64:67]
	v_mfma_f32_16x16x32_bf16 v[120:123], v[150:153], v[188:191], v[120:123]
	v_mfma_f32_16x16x32_bf16 v[112:115], v[158:161], v[188:191], v[112:115]
	v_mfma_f32_16x16x32_bf16 v[104:107], v[150:153], v[218:221], v[104:107]
	v_mfma_f32_16x16x32_bf16 v[96:99], v[158:161], v[218:221], v[96:99]
	v_mfma_f32_16x16x32_bf16 v[88:91], v[150:153], v[226:229], v[88:91]
	v_mfma_f32_16x16x32_bf16 v[80:83], v[158:161], v[226:229], v[80:83]
	v_mfma_f32_16x16x32_bf16 v[72:75], v[150:153], v[234:237], v[72:75]
	v_mfma_f32_16x16x32_bf16 v[64:67], v[158:161], v[234:237], v[64:67]
	v_mfma_f32_16x16x32_bf16 v[124:127], v[162:165], v[184:187], v[124:127]
	v_mfma_f32_16x16x32_bf16 v[116:119], v[176:179], v[184:187], v[116:119]
	v_mfma_f32_16x16x32_bf16 v[108:111], v[162:165], v[192:195], v[108:111]
	v_mfma_f32_16x16x32_bf16 v[100:103], v[176:179], v[192:195], v[100:103]
	v_mfma_f32_16x16x32_bf16 v[92:95], v[162:165], v[222:225], v[92:95]
	v_mfma_f32_16x16x32_bf16 v[84:87], v[176:179], v[222:225], v[84:87]
	v_mfma_f32_16x16x32_bf16 v[76:79], v[162:165], v[230:233], v[76:79]
	v_mfma_f32_16x16x32_bf16 v[68:71], v[176:179], v[230:233], v[68:71]
	v_mfma_f32_16x16x32_bf16 v[124:127], v[172:175], v[188:191], v[124:127]
	v_mfma_f32_16x16x32_bf16 v[116:119], v[180:183], v[188:191], v[116:119]
	v_mfma_f32_16x16x32_bf16 v[108:111], v[172:175], v[218:221], v[108:111]
	v_mfma_f32_16x16x32_bf16 v[100:103], v[180:183], v[218:221], v[100:103]
	v_mfma_f32_16x16x32_bf16 v[92:95], v[172:175], v[226:229], v[92:95]
	v_mfma_f32_16x16x32_bf16 v[84:87], v[180:183], v[226:229], v[84:87]
	v_mfma_f32_16x16x32_bf16 v[76:79], v[172:175], v[234:237], v[76:79]
	v_mfma_f32_16x16x32_bf16 v[68:71], v[180:183], v[234:237], v[68:71]
	s_setprio 0
	s_barrier
	s_add_i32 s78, s78, s54
	v_lshl_add_u64 v[166:167], s[76:77], 0, v[168:169]
	s_mov_b32 m0, s78
	ds_read_b128 v[184:187], v148 offset:16384
	ds_read_b128 v[188:191], v148 offset:17408
	ds_read_b128 v[192:195], v148 offset:18432
	ds_read_b128 v[218:221], v148 offset:19456
	ds_read_b128 v[222:225], v148 offset:20480
	ds_read_b128 v[226:229], v148 offset:21504
	ds_read_b128 v[230:233], v148 offset:22528
	ds_read_b128 v[234:237], v148 offset:23552
	global_load_lds_dwordx4 v[166:167], off
	s_add_i32 m0, s78, 0x2000
	v_lshl_add_u64 v[196:197], s[76:77], 0, v[128:129]
	s_add_u32 s76, s76, s48
	s_addc_u32 s77, s77, 0
	s_add_i32 s75, s75, s54
	global_load_lds_dwordx4 v[196:197], off
	v_lshl_add_u64 v[210:211], s[76:77], 0, v[168:169]
	s_mov_b32 m0, s75
	v_lshl_add_u64 v[212:213], s[76:77], 0, v[128:129]
	global_load_lds_dwordx4 v[210:211], off
	s_add_i32 m0, s75, 0x2000
	v_lshl_add_u64 v[238:239], s[22:23], 0, v[132:133]
	global_load_lds_dwordx4 v[212:213], off
	s_mov_b32 m0, s59
	v_lshl_add_u64 v[240:241], s[22:23], 0, v[130:131]
	global_load_lds_dwordx4 v[238:239], off
	s_mov_b32 m0, s60
	s_nop 0
	global_load_lds_dwordx4 v[240:241], off
	s_waitcnt vmcnt(8)
	s_waitcnt lgkmcnt(0)
	s_barrier
; #define PG8_STAGE(bufoff, gbase, voff) do { _Pragma("unroll") for (int _i = 0; _i < 2; ++_i) \
;         __builtin_amdgcn_global_load_lds((const unsigned*)((const char*)(gbase) + (voff)[_i]), (PG8_LAS unsigned*)(lds + (bufoff) + ldsw + _i * 8192), 16, 0, 0); } while (0)
; #define PG8_LDA(dst, b, h) do { _Pragma("unroll") for (int m = 0; m < 4; ++m) _Pragma("unroll") for (int k = 0; k < 2; ++k) dst[m][k] = *(const PG8_LAS bf16x8*)(lds + PG8_SA(b, h) + aoff + m * 2048 + k * 1024); } while (0)
; #define PG8_LDB(dst, b, h) do { _Pragma("unroll") for (int n = 0; n < 2; ++n) _Pragma("unroll") for (int k = 0; k < 2; ++k) dst[n][k] = *(const PG8_LAS bf16x8*)(lds + PG8_SB(b, h) + boff + n * 2048 + k * 1024); } while (0)
; #define PG8_MMA(ai, bj, At, Bt) do { __builtin_amdgcn_s_setprio(1); _Pragma("unroll") for (int m = 0; m < 4; ++m) _Pragma("unroll") for (int n = 0; n < 2; ++n) _Pragma("unroll") for (int k = 0; k < 2; ++k) \
;         acc[ai][bj][m][n] = __builtin_amdgcn_mfma_f32_16x16x32_bf16(Bt[n][k], At[m][k], acc[ai][bj][m][n], 0, 0, 0); __builtin_amdgcn_s_setprio(0); } while (0)
; #define PG8_WAIT_V(n) asm volatile("s_waitcnt vmcnt(" #n ")" ::: "memory")
; #define PG8_WAIT_L(n) asm volatile("s_waitcnt lgkmcnt(" #n ")" ::: "memory")
; #define PG8_BAR __builtin_amdgcn_s_barrier()
; #define PG8_SCHED __builtin_amdgcn_sched_barrier(0)
; template <class Epi, class Sched, bool ALIGN_EPI = false, bool SP2 = false>
; __device__ __forceinline__ void gemm_phase(PG8_LAS unsigned char* lds, const Gemm g, const Sched& S, const Epi& E) {
;     ...
;             PG8_WAIT_V(8); PG8_WAIT_L(0); PG8_BAR; PG8_MMA(1, 0, At, B0); PG8_MMA(1, 1, At, B1); PG8_BAR; PG8_SCHED;
;             PG8_LDB(B0, 1, 0); PG8_LDB(B1, 1, 1); PG8_SCHED; PG8_LDA(At, 1, 0); PG8_STAGE(PG8_SA(0, 1), a2 + hstepA, voffA);
;             PG8_WAIT_V(8); PG8_WAIT_L(0); PG8_BAR; PG8_MMA(0, 0, At, B0); PG8_MMA(0, 1, At, B1); PG8_BAR; PG8_SCHED;
	s_setprio 1
	s_waitcnt lgkmcnt(0)
	v_mfma_f32_16x16x32_bf16 v[56:59], v[140:143], v[184:187], v[56:59]
	v_mfma_f32_16x16x32_bf16 v[48:51], v[154:157], v[184:187], v[48:51]
	v_mfma_f32_16x16x32_bf16 v[40:43], v[140:143], v[192:195], v[40:43]
	v_mfma_f32_16x16x32_bf16 v[32:35], v[154:157], v[192:195], v[32:35]
	v_mfma_f32_16x16x32_bf16 v[24:27], v[140:143], v[222:225], v[24:27]
	v_mfma_f32_16x16x32_bf16 v[16:19], v[154:157], v[222:225], v[16:19]
	v_mfma_f32_16x16x32_bf16 v[8:11], v[140:143], v[230:233], v[8:11]
	v_mfma_f32_16x16x32_bf16 v[4:7], v[154:157], v[230:233], v[4:7]
	v_mfma_f32_16x16x32_bf16 v[56:59], v[150:153], v[188:191], v[56:59]
	v_mfma_f32_16x16x32_bf16 v[48:51], v[158:161], v[188:191], v[48:51]
	v_mfma_f32_16x16x32_bf16 v[40:43], v[150:153], v[218:221], v[40:43]
	v_mfma_f32_16x16x32_bf16 v[32:35], v[158:161], v[218:221], v[32:35]
	v_mfma_f32_16x16x32_bf16 v[24:27], v[150:153], v[226:229], v[24:27]
	v_mfma_f32_16x16x32_bf16 v[16:19], v[158:161], v[226:229], v[16:19]
	v_mfma_f32_16x16x32_bf16 v[8:11], v[150:153], v[234:237], v[8:11]
	v_mfma_f32_16x16x32_bf16 v[4:7], v[158:161], v[234:237], v[4:7]
	v_mfma_f32_16x16x32_bf16 v[60:63], v[162:165], v[184:187], v[60:63]
	v_mfma_f32_16x16x32_bf16 v[52:55], v[176:179], v[184:187], v[52:55]
	v_mfma_f32_16x16x32_bf16 v[44:47], v[162:165], v[192:195], v[44:47]
	v_mfma_f32_16x16x32_bf16 v[36:39], v[176:179], v[192:195], v[36:39]
	v_mfma_f32_16x16x32_bf16 v[28:31], v[162:165], v[222:225], v[28:31]
	v_mfma_f32_16x16x32_bf16 v[20:23], v[176:179], v[222:225], v[20:23]
	v_mfma_f32_16x16x32_bf16 v[12:15], v[162:165], v[230:233], v[12:15]
	v_mfma_f32_16x16x32_bf16 v[0:3], v[176:179], v[230:233], v[0:3]
	v_mfma_f32_16x16x32_bf16 v[60:63], v[172:175], v[188:191], v[60:63]
	v_mfma_f32_16x16x32_bf16 v[52:55], v[180:183], v[188:191], v[52:55]
	v_mfma_f32_16x16x32_bf16 v[44:47], v[172:175], v[218:221], v[44:47]
	v_mfma_f32_16x16x32_bf16 v[36:39], v[180:183], v[218:221], v[36:39]
	v_mfma_f32_16x16x32_bf16 v[28:31], v[172:175], v[226:229], v[28:31]
	v_mfma_f32_16x16x32_bf16 v[20:23], v[180:183], v[226:229], v[20:23]
	v_mfma_f32_16x16x32_bf16 v[12:15], v[172:175], v[234:237], v[12:15]
	v_mfma_f32_16x16x32_bf16 v[0:3], v[180:183], v[234:237], v[0:3]
	s_setprio 0
	s_barrier
	s_add_i32 s75, 0, 0x18000
	v_add_u32_e32 v144, s75, v146
	s_add_i32 s76, 0, 0x1c000
	ds_read_b128 v[140:143], v144
	ds_read_b128 v[150:153], v144 offset:1024
	ds_read_b128 v[154:157], v144 offset:2048
	ds_read_b128 v[158:161], v144 offset:3072
	v_add_u32_e32 v144, s76, v146
	ds_read_b128 v[162:165], v144
	ds_read_b128 v[172:175], v144 offset:1024
	ds_read_b128 v[176:179], v144 offset:2048
	ds_read_b128 v[180:183], v144 offset:3072
	s_add_u32 s22, s22, s28
	s_addc_u32 s23, s23, 0
	s_mov_b32 m0, s61
	v_lshl_add_u64 v[242:243], s[22:23], 0, v[132:133]
	ds_read_b128 v[184:187], v148 offset:32768
	ds_read_b128 v[188:191], v148 offset:33792
	ds_read_b128 v[192:195], v148 offset:34816
	ds_read_b128 v[218:221], v148 offset:35840
	ds_read_b128 v[222:225], v148 offset:36864
	ds_read_b128 v[226:229], v148 offset:37888
	ds_read_b128 v[230:233], v148 offset:38912
	ds_read_b128 v[234:237], v148 offset:39936
	global_load_lds_dwordx4 v[242:243], off
	v_lshl_add_u64 v[242:243], s[22:23], 0, v[130:131]
	s_mov_b32 m0, s62
	s_nop 0
	global_load_lds_dwordx4 v[242:243], off
	s_waitcnt vmcnt(8)
	s_waitcnt lgkmcnt(0)
	s_barrier
	s_setprio 1
	s_waitcnt lgkmcnt(0)
	v_mfma_f32_16x16x32_bf16 v[120:123], v[140:143], v[184:187], v[120:123]
	v_mfma_f32_16x16x32_bf16 v[112:115], v[154:157], v[184:187], v[112:115]
	v_mfma_f32_16x16x32_bf16 v[104:107], v[140:143], v[192:195], v[104:107]
	v_mfma_f32_16x16x32_bf16 v[96:99], v[154:157], v[192:195], v[96:99]
	v_mfma_f32_16x16x32_bf16 v[88:91], v[140:143], v[222:225], v[88:91]
	v_mfma_f32_16x16x32_bf16 v[80:83], v[154:157], v[222:225], v[80:83]
	v_mfma_f32_16x16x32_bf16 v[72:75], v[140:143], v[230:233], v[72:75]
	v_mfma_f32_16x16x32_bf16 v[64:67], v[154:157], v[230:233], v[64:67]
	v_mfma_f32_16x16x32_bf16 v[120:123], v[150:153], v[188:191], v[120:123]
	v_mfma_f32_16x16x32_bf16 v[112:115], v[158:161], v[188:191], v[112:115]
	v_mfma_f32_16x16x32_bf16 v[104:107], v[150:153], v[218:221], v[104:107]
	v_mfma_f32_16x16x32_bf16 v[96:99], v[158:161], v[218:221], v[96:99]
	v_mfma_f32_16x16x32_bf16 v[88:91], v[150:153], v[226:229], v[88:91]
	v_mfma_f32_16x16x32_bf16 v[80:83], v[158:161], v[226:229], v[80:83]
	v_mfma_f32_16x16x32_bf16 v[72:75], v[150:153], v[234:237], v[72:75]
	v_mfma_f32_16x16x32_bf16 v[64:67], v[158:161], v[234:237], v[64:67]
	v_mfma_f32_16x16x32_bf16 v[124:127], v[162:165], v[184:187], v[124:127]
	v_mfma_f32_16x16x32_bf16 v[116:119], v[176:179], v[184:187], v[116:119]
	v_mfma_f32_16x16x32_bf16 v[108:111], v[162:165], v[192:195], v[108:111]
	v_mfma_f32_16x16x32_bf16 v[100:103], v[176:179], v[192:195], v[100:103]
	v_mfma_f32_16x16x32_bf16 v[92:95], v[162:165], v[222:225], v[92:95]
	v_mfma_f32_16x16x32_bf16 v[84:87], v[176:179], v[222:225], v[84:87]
	v_mfma_f32_16x16x32_bf16 v[76:79], v[162:165], v[230:233], v[76:79]
	v_mfma_f32_16x16x32_bf16 v[68:71], v[176:179], v[230:233], v[68:71]
	v_mfma_f32_16x16x32_bf16 v[124:127], v[172:175], v[188:191], v[124:127]
	v_mfma_f32_16x16x32_bf16 v[116:119], v[180:183], v[188:191], v[116:119]
	v_mfma_f32_16x16x32_bf16 v[108:111], v[172:175], v[218:221], v[108:111]
	v_mfma_f32_16x16x32_bf16 v[100:103], v[180:183], v[218:221], v[100:103]
	v_mfma_f32_16x16x32_bf16 v[92:95], v[172:175], v[226:229], v[92:95]
	v_mfma_f32_16x16x32_bf16 v[84:87], v[180:183], v[226:229], v[84:87]
	v_mfma_f32_16x16x32_bf16 v[76:79], v[172:175], v[234:237], v[76:79]
	v_mfma_f32_16x16x32_bf16 v[68:71], v[180:183], v[234:237], v[68:71]
	s_setprio 0
	s_barrier
; #define PG8_STAGE(bufoff, gbase, voff) do { _Pragma("unroll") for (int _i = 0; _i < 2; ++_i) \
;         __builtin_amdgcn_global_load_lds((const unsigned*)((const char*)(gbase) + (voff)[_i]), (PG8_LAS unsigned*)(lds + (bufoff) + ldsw + _i * 8192), 16, 0, 0); } while (0)
; #define PG8_LDA(dst, b, h) do { _Pragma("unroll") for (int m = 0; m < 4; ++m) _Pragma("unroll") for (int k = 0; k < 2; ++k) dst[m][k] = *(const PG8_LAS bf16x8*)(lds + PG8_SA(b, h) + aoff + m * 2048 + k * 1024); } while (0)
; #define PG8_MMA(ai, bj, At, Bt) do { __builtin_amdgcn_s_setprio(1); _Pragma("unroll") for (int m = 0; m < 4; ++m) _Pragma("unroll") for (int n = 0; n < 2; ++n) _Pragma("unroll") for (int k = 0; k < 2; ++k) \
;         acc[ai][bj][m][n] = __builtin_amdgcn_mfma_f32_16x16x32_bf16(Bt[n][k], At[m][k], acc[ai][bj][m][n], 0, 0, 0); __builtin_amdgcn_s_setprio(0); } while (0)
; #define PG8_WAIT_V(n) asm volatile("s_waitcnt vmcnt(" #n ")" ::: "memory")
; #define PG8_WAIT_L(n) asm volatile("s_waitcnt lgkmcnt(" #n ")" ::: "memory")
; #define PG8_BAR __builtin_amdgcn_s_barrier()
; #define PG8_SCHED __builtin_amdgcn_sched_barrier(0)
; template <class Epi, class Sched, bool ALIGN_EPI = false, bool SP2 = false>
; __device__ __forceinline__ void gemm_phase(PG8_LAS unsigned char* lds, const Gemm g, const Sched& S, const Epi& E) {
;     ...
;         for (int t = 0; t < nt; t += 2) {
;     ...
;             PG8_LDA(At, 1, 1); PG8_STAGE(PG8_SB(1, 0), b3, voffB); PG8_STAGE(PG8_SB(1, 1), b3 + hstep, voffB); PG8_STAGE(PG8_SA(1, 0), a3, voffA);
;             PG8_WAIT_V(8); PG8_WAIT_L(0); PG8_BAR; PG8_MMA(1, 0, At, B0); PG8_MMA(1, 1, At, B1); PG8_BAR; PG8_SCHED;
	s_add_i32 s22, s75, s54
	v_lshl_add_u64 v[166:167], v[166:167], 0, s[10:11]
	s_mov_b32 m0, s22
	ds_read_b128 v[184:187], v148 offset:49152
	ds_read_b128 v[188:191], v148 offset:50176
	ds_read_b128 v[192:195], v148 offset:51200
	ds_read_b128 v[218:221], v148 offset:52224
	ds_read_b128 v[222:225], v148 offset:53248
	ds_read_b128 v[226:229], v148 offset:54272
	ds_read_b128 v[230:233], v148 offset:55296
	ds_read_b128 v[234:237], v148 offset:56320
	global_load_lds_dwordx4 v[166:167], off
	v_lshl_add_u64 v[166:167], v[196:197], 0, s[10:11]
	s_add_i32 m0, s22, 0x2000
	s_add_i32 s22, s76, s54
	global_load_lds_dwordx4 v[166:167], off
	v_lshl_add_u64 v[166:167], v[210:211], 0, s[10:11]
	s_mov_b32 m0, s22
	s_nop 0
	global_load_lds_dwordx4 v[166:167], off
	v_lshl_add_u64 v[166:167], v[212:213], 0, s[10:11]
	s_add_i32 m0, s22, 0x2000
	s_nop 0
	global_load_lds_dwordx4 v[166:167], off
	v_lshl_add_u64 v[166:167], v[238:239], 0, s[10:11]
	s_mov_b32 m0, s63
	s_nop 0
	global_load_lds_dwordx4 v[166:167], off
	v_lshl_add_u64 v[166:167], v[240:241], 0, s[10:11]
	s_mov_b32 m0, s64
	s_nop 0
	global_load_lds_dwordx4 v[166:167], off
	s_waitcnt vmcnt(8)
	s_waitcnt lgkmcnt(0)
	s_barrier
	s_setprio 1
	s_waitcnt lgkmcnt(0)
	v_mfma_f32_16x16x32_bf16 v[56:59], v[140:143], v[184:187], v[56:59]
	v_mfma_f32_16x16x32_bf16 v[48:51], v[154:157], v[184:187], v[48:51]
	v_mfma_f32_16x16x32_bf16 v[40:43], v[140:143], v[192:195], v[40:43]
	v_mfma_f32_16x16x32_bf16 v[32:35], v[154:157], v[192:195], v[32:35]
	v_mfma_f32_16x16x32_bf16 v[24:27], v[140:143], v[222:225], v[24:27]
	v_mfma_f32_16x16x32_bf16 v[16:19], v[154:157], v[222:225], v[16:19]
	v_mfma_f32_16x16x32_bf16 v[8:11], v[140:143], v[230:233], v[8:11]
	v_mfma_f32_16x16x32_bf16 v[4:7], v[154:157], v[230:233], v[4:7]
	v_mfma_f32_16x16x32_bf16 v[56:59], v[150:153], v[188:191], v[56:59]
	v_mfma_f32_16x16x32_bf16 v[48:51], v[158:161], v[188:191], v[48:51]
	v_mfma_f32_16x16x32_bf16 v[40:43], v[150:153], v[218:221], v[40:43]
	v_mfma_f32_16x16x32_bf16 v[32:35], v[158:161], v[218:221], v[32:35]
	v_mfma_f32_16x16x32_bf16 v[24:27], v[150:153], v[226:229], v[24:27]
	v_mfma_f32_16x16x32_bf16 v[16:19], v[158:161], v[226:229], v[16:19]
	v_mfma_f32_16x16x32_bf16 v[8:11], v[150:153], v[234:237], v[8:11]
	v_mfma_f32_16x16x32_bf16 v[4:7], v[158:161], v[234:237], v[4:7]
	v_mfma_f32_16x16x32_bf16 v[60:63], v[162:165], v[184:187], v[60:63]
	v_mfma_f32_16x16x32_bf16 v[52:55], v[176:179], v[184:187], v[52:55]
	v_mfma_f32_16x16x32_bf16 v[44:47], v[162:165], v[192:195], v[44:47]
	v_mfma_f32_16x16x32_bf16 v[36:39], v[176:179], v[192:195], v[36:39]
	v_mfma_f32_16x16x32_bf16 v[28:31], v[162:165], v[222:225], v[28:31]
	v_mfma_f32_16x16x32_bf16 v[20:23], v[176:179], v[222:225], v[20:23]
	v_mfma_f32_16x16x32_bf16 v[12:15], v[162:165], v[230:233], v[12:15]
	v_mfma_f32_16x16x32_bf16 v[0:3], v[176:179], v[230:233], v[0:3]
	v_mfma_f32_16x16x32_bf16 v[60:63], v[172:175], v[188:191], v[60:63]
	v_mfma_f32_16x16x32_bf16 v[52:55], v[180:183], v[188:191], v[52:55]
	v_mfma_f32_16x16x32_bf16 v[44:47], v[172:175], v[218:221], v[44:47]
	v_mfma_f32_16x16x32_bf16 v[36:39], v[180:183], v[218:221], v[36:39]
	v_mfma_f32_16x16x32_bf16 v[28:31], v[172:175], v[226:229], v[28:31]
	v_mfma_f32_16x16x32_bf16 v[20:23], v[180:183], v[226:229], v[20:23]
	v_mfma_f32_16x16x32_bf16 v[12:15], v[172:175], v[234:237], v[12:15]
	v_mfma_f32_16x16x32_bf16 v[0:3], v[180:183], v[234:237], v[0:3]
	s_setprio 0
	s_barrier
	s_add_u32 s4, s4, 0x100
	s_addc_u32 s5, s5, 0
	s_add_u32 s20, s20, 0x100
	s_addc_u32 s21, s21, 0
	s_cmp_ge_u32 s74, s65
	s_mov_b32 s22, s74
	s_cbranch_scc0 .LBB0_1168
